# v106 plus the individually neutral trims together: add+dpp fusion with empty lgkm waits removed, attention peephole, GATE x-load hoist
# speedup vs baseline: 1.0194x; 1.0194x over previous
.LBB0_685:
	v_lshl_or_b32 v0, s38, 5, v202
	v_mad_u32_u24 v0, v0, s30, v208
	ds_read_b128 v[2:5], v0
	ds_read_b128 v[6:9], v0 offset:32
	ds_read_b128 v[222:225], v0 offset:64
	ds_read_b128 v[226:229], v0 offset:96
	ds_read_b128 v[230:233], v0 offset:128
	ds_read_b128 v[234:237], v0 offset:160
	s_waitcnt lgkmcnt(5)
	v_mfma_f32_32x32x16_bf16 v[80:95], v[2:5], v[148:151], 0
	ds_read_b128 v[2:5], v0 offset:192
	s_waitcnt lgkmcnt(5)
	v_mfma_f32_32x32x16_bf16 v[80:95], v[6:9], v[96:99], v[80:95]
	ds_read_b128 v[6:9], v0 offset:224
	s_waitcnt lgkmcnt(5)
	v_mfma_f32_32x32x16_bf16 v[80:95], v[222:225], v[100:103], v[80:95]
	ds_read_b128 v[222:225], v0 offset:256
	s_waitcnt lgkmcnt(5)
	v_mfma_f32_32x32x16_bf16 v[80:95], v[226:229], v[104:107], v[80:95]
	ds_read_b128 v[226:229], v0 offset:288
	s_waitcnt lgkmcnt(5)
	v_mfma_f32_32x32x16_bf16 v[80:95], v[230:233], v[108:111], v[80:95]
	ds_read_b128 v[230:233], v0 offset:320
	s_waitcnt lgkmcnt(5)
	v_mfma_f32_32x32x16_bf16 v[80:95], v[234:237], v[112:115], v[80:95]
	ds_read_b128 v[234:237], v0 offset:352
	s_waitcnt lgkmcnt(5)
	v_mfma_f32_32x32x16_bf16 v[80:95], v[2:5], v[116:119], v[80:95]
	s_waitcnt lgkmcnt(4)
	v_mfma_f32_32x32x16_bf16 v[80:95], v[6:9], v[120:123], v[80:95]
	s_waitcnt lgkmcnt(3)
	v_mfma_f32_32x32x16_bf16 v[80:95], v[222:225], v[124:127], v[80:95]
	s_waitcnt lgkmcnt(2)
	v_mfma_f32_32x32x16_bf16 v[80:95], v[226:229], v[128:131], v[80:95]
	s_waitcnt lgkmcnt(1)
	v_mfma_f32_32x32x16_bf16 v[80:95], v[230:233], v[132:135], v[80:95]
	s_waitcnt lgkmcnt(0)
	v_mfma_f32_32x32x16_bf16 v[80:95], v[234:237], v[140:143], v[80:95]
	s_nop 11
	v_max_f32_e32 v0, v80, v81
	v_max3_f32 v0, v0, v82, v83
	v_max3_f32 v0, v0, v84, v85
	v_max3_f32 v0, v0, v86, v87
	v_max3_f32 v0, v0, v88, v89
	v_max3_f32 v0, v0, v90, v91
	v_max3_f32 v0, v0, v92, v93
	v_max3_f32 v0, v0, v94, v95
	v_mov_b32_e32 v2, v0
	s_nop 1
	v_permlane32_swap_b32_e32 v2, v0
	s_waitcnt lgkmcnt(0)
	v_max_f32_e32 v0, v0, v2
	v_mul_f32_e32 v0, 0x3dd53b94, v0
	v_add_f32_e32 v250, 0xc1000000, v0
	v_cmp_gt_f32_e32 vcc, v250, v198
	s_cbranch_vccz .LBB0_684
	v_max_f32_e32 v0, v0, v0
	v_max_f32_e32 v2, v198, v198
	v_max_f32_e32 v2, v2, v0
	v_sub_f32_e32 v0, v198, v2
	v_exp_f32_e32 v0, v0
	v_mov_b32_e32 v198, v2
	v_pk_mul_f32 v[78:79], v[78:79], v[0:1] op_sel_hi:[1,0]
	v_pk_mul_f32 v[76:77], v[76:77], v[0:1] op_sel_hi:[1,0]
	v_pk_mul_f32 v[74:75], v[74:75], v[0:1] op_sel_hi:[1,0]
	v_pk_mul_f32 v[72:73], v[72:73], v[0:1] op_sel_hi:[1,0]
	v_pk_mul_f32 v[70:71], v[70:71], v[0:1] op_sel_hi:[1,0]
	v_pk_mul_f32 v[68:69], v[68:69], v[0:1] op_sel_hi:[1,0]
	v_pk_mul_f32 v[66:67], v[66:67], v[0:1] op_sel_hi:[1,0]
	v_pk_mul_f32 v[64:65], v[64:65], v[0:1] op_sel_hi:[1,0]
	v_pk_mul_f32 v[62:63], v[62:63], v[0:1] op_sel_hi:[1,0]
	v_pk_mul_f32 v[60:61], v[60:61], v[0:1] op_sel_hi:[1,0]
	v_pk_mul_f32 v[58:59], v[58:59], v[0:1] op_sel_hi:[1,0]
	v_pk_mul_f32 v[56:57], v[56:57], v[0:1] op_sel_hi:[1,0]
	v_pk_mul_f32 v[54:55], v[54:55], v[0:1] op_sel_hi:[1,0]
	v_pk_mul_f32 v[52:53], v[52:53], v[0:1] op_sel_hi:[1,0]
	v_pk_mul_f32 v[50:51], v[50:51], v[0:1] op_sel_hi:[1,0]
	v_pk_mul_f32 v[48:49], v[48:49], v[0:1] op_sel_hi:[1,0]
	v_pk_mul_f32 v[46:47], v[46:47], v[0:1] op_sel_hi:[1,0]
	v_pk_mul_f32 v[44:45], v[44:45], v[0:1] op_sel_hi:[1,0]
	v_pk_mul_f32 v[42:43], v[42:43], v[0:1] op_sel_hi:[1,0]
	v_pk_mul_f32 v[40:41], v[40:41], v[0:1] op_sel_hi:[1,0]
	v_pk_mul_f32 v[38:39], v[38:39], v[0:1] op_sel_hi:[1,0]
	v_pk_mul_f32 v[36:37], v[36:37], v[0:1] op_sel_hi:[1,0]
	v_pk_mul_f32 v[34:35], v[34:35], v[0:1] op_sel_hi:[1,0]
	v_pk_mul_f32 v[32:33], v[32:33], v[0:1] op_sel_hi:[1,0]
	v_pk_mul_f32 v[30:31], v[30:31], v[0:1] op_sel_hi:[1,0]
	v_pk_mul_f32 v[28:29], v[28:29], v[0:1] op_sel_hi:[1,0]
	v_pk_mul_f32 v[26:27], v[26:27], v[0:1] op_sel_hi:[1,0]
	v_pk_mul_f32 v[24:25], v[24:25], v[0:1] op_sel_hi:[1,0]
	v_pk_mul_f32 v[22:23], v[22:23], v[0:1] op_sel_hi:[1,0]
	v_pk_mul_f32 v[20:21], v[20:21], v[0:1] op_sel_hi:[1,0]
	v_pk_mul_f32 v[18:19], v[18:19], v[0:1] op_sel_hi:[1,0]
	v_pk_mul_f32 v[16:17], v[16:17], v[0:1] op_sel_hi:[1,0]
	v_mul_f32_e32 v193, v193, v0
	s_branch .LBB0_684
